# adds: attention row-max cross-half exchange via v_permlane32_swap instead of ds_bpermute + lgkmcnt wait (no LDS round trip per step)
# baseline (speedup 1.0000x reference)
; __device__ __forceinline__ void attn_tile(LAS unsigned char* lds, int bo, const bf16x8 (&qr)[4], f32x16& o0, f32x16& o1, float& mrun, float& lrun, int t, int qlo, int r32, int hi) {
;     ...
;     float mx = fmaxf(p0[0], p1[0]);
; #pragma unroll
;     for (int r = 1; r < 16; ++r) mx = fmaxf(mx, fmaxf(p0[r], p1[r]));
;     mx = fmaxf(mx, __shfl_xor(mx, 32));
;     if (__any(mx > mrun)) {
;         const float mnew = fmaxf(mrun, mx);
;         const float alpha = __builtin_amdgcn_exp2f(mrun - mnew);
;         mrun = mnew; lrun *= alpha;
; #pragma unroll
;         for (int r = 0; r < 16; ++r) { o0[r] *= alpha; o1[r] *= alpha; }
;     }
.LBB0_631:
	s_nop 10
	v_max3_f32 v0, v48, v49, v50
	v_max3_f32 v2, v64, v65, v66
	v_max3_f32 v0, v0, v51, v52
	v_max3_f32 v2, v2, v67, v68
	v_max3_f32 v0, v0, v53, v54
	v_max3_f32 v2, v2, v69, v70
	v_max3_f32 v0, v0, v55, v56
	v_max3_f32 v2, v2, v71, v72
	v_max3_f32 v0, v0, v57, v58
	v_max3_f32 v2, v2, v73, v74
	v_max3_f32 v0, v0, v59, v60
	v_max3_f32 v2, v2, v75, v76
	v_max3_f32 v0, v0, v61, v62
	v_max3_f32 v2, v2, v77, v78
	v_max3_f32 v0, v0, v63, v79
	v_max_f32_e32 v0, v0, v2
	v_mov_b32_e32 v2, v0
	s_nop 1
	v_permlane32_swap_b32_e32 v2, v0
	v_max_f32_e32 v0, v0, v2
	v_cmp_gt_f32_e32 vcc, v0, v165
	s_cbranch_vccz .LBB0_633
	v_max_f32_e32 v0, v0, v0
	v_max_f32_e32 v2, v165, v165
	v_max_f32_e32 v2, v2, v0
	v_sub_f32_e32 v0, v165, v2
	v_exp_f32_e32 v0, v0
	v_mov_b32_e32 v165, v2
	v_mul_f32_e32 v164, v164, v0
	v_pk_mul_f32 v[46:47], v[46:47], v[0:1] op_sel_hi:[1,0]
	v_pk_mul_f32 v[44:45], v[44:45], v[0:1] op_sel_hi:[1,0]
	v_pk_mul_f32 v[42:43], v[42:43], v[0:1] op_sel_hi:[1,0]
	v_pk_mul_f32 v[40:41], v[40:41], v[0:1] op_sel_hi:[1,0]
	v_pk_mul_f32 v[38:39], v[38:39], v[0:1] op_sel_hi:[1,0]
	v_pk_mul_f32 v[36:37], v[36:37], v[0:1] op_sel_hi:[1,0]
	v_pk_mul_f32 v[34:35], v[34:35], v[0:1] op_sel_hi:[1,0]
	v_pk_mul_f32 v[32:33], v[32:33], v[0:1] op_sel_hi:[1,0]
	v_pk_mul_f32 v[30:31], v[30:31], v[0:1] op_sel_hi:[1,0]
	v_pk_mul_f32 v[28:29], v[28:29], v[0:1] op_sel_hi:[1,0]
	v_pk_mul_f32 v[26:27], v[26:27], v[0:1] op_sel_hi:[1,0]
	v_pk_mul_f32 v[24:25], v[24:25], v[0:1] op_sel_hi:[1,0]
	v_pk_mul_f32 v[22:23], v[22:23], v[0:1] op_sel_hi:[1,0]
	v_pk_mul_f32 v[20:21], v[20:21], v[0:1] op_sel_hi:[1,0]
	v_pk_mul_f32 v[18:19], v[18:19], v[0:1] op_sel_hi:[1,0]
	v_pk_mul_f32 v[16:17], v[16:17], v[0:1] op_sel_hi:[1,0]
